# speedup vs baseline: 1.0568x; 1.0091x over previous
; __device__ __forceinline__ unsigned xb_ld(unsigned* p) { return __hip_atomic_load(p, __ATOMIC_RELAXED, __HIP_MEMORY_SCOPE_AGENT); }
; __device__ __forceinline__ void grid_barrier_impl(int wave, unsigned G, unsigned xcc, volatile LAS unsigned* st) {
;     ...
;         const unsigned gen = xb_ld(&g_xb[XB_GEN(xcc)]);
;         const unsigned old = __hip_atomic_fetch_add(&g_xb[XB_CNT(xcc)], 1u, __ATOMIC_ACQ_REL, __HIP_MEMORY_SCOPE_AGENT);
.LBB0_204:
	global_load_dword v2, v195, s[94:95] sc1
	s_mov_b64 s[38:39], exec
	v_mbcnt_lo_u32_b32 v3, s38, 0
	v_mbcnt_hi_u32_b32 v3, s39, v3
	v_cmp_eq_u32_e32 vcc, 0, v3
	s_and_saveexec_b64 s[40:41], vcc
	s_cbranch_execz .LBB0_206
	s_bcnt1_i32_b64 s38, s[38:39]
	v_mov_b32_e32 v4, s38
	v_readlane_b32 s38, v253, 42
	v_readlane_b32 s39, v253, 43
	s_nop 0
	s_waitcnt vmcnt(0) lgkmcnt(0)
	s_nop 2
	global_atomic_add v4, v195, v4, s[38:39] sc0
	s_waitcnt vmcnt(0)
	s_nop 0

; __device__ __forceinline__ unsigned xb_ld(unsigned* p) { return __hip_atomic_load(p, __ATOMIC_RELAXED, __HIP_MEMORY_SCOPE_AGENT); }
; __device__ __forceinline__ void grid_barrier_impl(int wave, unsigned G, unsigned xcc, volatile LAS unsigned* st) {
;     ...
;         if (old == nloc - 1u) {
;             __hip_atomic_store(&g_xb[XB_CNT(xcc)], 0u, __ATOMIC_RELAXED, __HIP_MEMORY_SCOPE_AGENT);
;             __builtin_amdgcn_fence(__ATOMIC_RELEASE, "agent");
;             asm volatile("s_waitcnt vmcnt(0)" ::: "memory");
;             const unsigned tg = xb_ld(&g_xb[XB_TGEN]);
;             const unsigned o2 = __hip_atomic_fetch_add(&g_xb[XB_TCNT], 1u, __ATOMIC_ACQ_REL, __HIP_MEMORY_SCOPE_AGENT);
.LBB0_210:
	s_andn2_saveexec_b64 s[38:39], s[38:39]
	s_cbranch_execz .LBB0_223
	v_readlane_b32 s40, v253, 42
	v_readlane_b32 s41, v253, 43
	s_mov_b64 s[38:39], exec
	s_waitcnt vmcnt(0)
	v_mbcnt_lo_u32_b32 v2, s38, 0
	v_mbcnt_hi_u32_b32 v2, s39, v2
	v_cmp_eq_u32_e32 vcc, 0, v2
	global_store_dword v195, v195, s[40:41] sc1
	buffer_wbl2 sc1
	s_waitcnt vmcnt(0) lgkmcnt(0)
	s_waitcnt vmcnt(0)
	s_getpc_b64 s[40:41]
	s_add_u32 s40, s40, g_xb@rel32@lo+12548
	s_addc_u32 s41, s41, g_xb@rel32@hi+12556
	global_load_dword v1, v195, s[40:41] sc1
	s_and_saveexec_b64 s[40:41], vcc
	s_cbranch_execz .LBB0_213
	s_bcnt1_i32_b64 s42, s[38:39]
	s_getpc_b64 s[38:39]
	s_add_u32 s38, s38, g_xb@rel32@lo+12292
	s_addc_u32 s39, s39, g_xb@rel32@hi+12300
	v_mov_b32_e32 v3, s42
	s_nop 0
	s_waitcnt vmcnt(0)
	global_atomic_add v3, v195, v3, s[38:39] sc0
	s_waitcnt vmcnt(0)
	s_nop 0

; __device__ __forceinline__ void grid_barrier_impl(int wave, unsigned G, unsigned xcc, volatile LAS unsigned* st) {
;     ...
;             if (o2 == nx - 1u) { __hip_atomic_store(&g_xb[XB_TCNT], 0u, __ATOMIC_RELAXED, __HIP_MEMORY_SCOPE_AGENT); __hip_atomic_fetch_add(&g_xb[XB_TGEN], 1u, __ATOMIC_RELEASE, __HIP_MEMORY_SCOPE_AGENT); }
.LBB0_216:
	s_andn2_saveexec_b64 s[38:39], s[38:39]
	s_cbranch_execz .LBB0_220
	s_mov_b64 s[40:41], exec
	v_mbcnt_lo_u32_b32 v0, s40, 0
	v_mbcnt_hi_u32_b32 v0, s41, v0
	s_getpc_b64 s[42:43]
	s_add_u32 s42, s42, g_xb@rel32@lo+12292
	s_addc_u32 s43, s43, g_xb@rel32@hi+12300
	v_cmp_eq_u32_e32 vcc, 0, v0
	global_store_dword v195, v195, s[42:43] sc1
	s_and_saveexec_b64 s[42:43], vcc
	s_cbranch_execz .LBB0_219
	s_bcnt1_i32_b64 s44, s[40:41]
	s_getpc_b64 s[40:41]
	s_add_u32 s40, s40, g_xb@rel32@lo+12548
	s_addc_u32 s41, s41, g_xb@rel32@hi+12556
	v_mov_b32_e32 v0, s44
	s_nop 0
	s_waitcnt vmcnt(0)
	global_atomic_add v195, v0, s[40:41]

; __device__ __forceinline__ void grid_barrier_impl(int wave, unsigned G, unsigned xcc, volatile LAS unsigned* st) {
;     ...
;             __builtin_amdgcn_fence(__ATOMIC_ACQUIRE, "agent");
;             __hip_atomic_fetch_add(&g_xb[XB_GEN(xcc)], 1u, __ATOMIC_RELEASE, __HIP_MEMORY_SCOPE_AGENT);
.LBB0_220:
	s_or_b64 exec, exec, s[38:39]
	s_mov_b64 s[38:39], exec
	v_mbcnt_lo_u32_b32 v0, s38, 0
	v_mbcnt_hi_u32_b32 v0, s39, v0
	v_cmp_eq_u32_e32 vcc, 0, v0
	s_waitcnt vmcnt(0)
	buffer_inv sc1
	s_and_saveexec_b64 s[40:41], vcc
	s_cbranch_execz .LBB0_222
	s_bcnt1_i32_b64 s38, s[38:39]
	v_mov_b32_e32 v0, s38
	s_nop 0
	global_atomic_add v195, v0, s[94:95]

; __device__ __forceinline__ unsigned xb_ld(unsigned* p) { return __hip_atomic_load(p, __ATOMIC_RELAXED, __HIP_MEMORY_SCOPE_AGENT); }
; __device__ __forceinline__ void grid_barrier_impl(int wave, unsigned G, unsigned xcc, volatile LAS unsigned* st) {
;     ...
;         const unsigned gen = xb_ld(&g_xb[XB_GEN(xcc)]);
;         const unsigned old = __hip_atomic_fetch_add(&g_xb[XB_CNT(xcc)], 1u, __ATOMIC_ACQ_REL, __HIP_MEMORY_SCOPE_AGENT);
.LBB0_251:
	global_load_dword v2, v195, s[94:95] sc1
	s_mov_b64 s[40:41], exec
	v_mbcnt_lo_u32_b32 v3, s40, 0
	v_mbcnt_hi_u32_b32 v3, s41, v3
	v_cmp_eq_u32_e32 vcc, 0, v3
	s_and_saveexec_b64 s[42:43], vcc
	s_cbranch_execz .LBB0_253
	s_bcnt1_i32_b64 s38, s[40:41]
	v_mov_b32_e32 v4, s38
	v_readlane_b32 s38, v253, 42
	v_readlane_b32 s39, v253, 43
	s_nop 0
	s_waitcnt vmcnt(0) lgkmcnt(0)
	s_nop 2
	global_atomic_add v4, v195, v4, s[38:39] sc0
	s_waitcnt vmcnt(0)
	s_nop 0

; __device__ __forceinline__ unsigned xb_ld(unsigned* p) { return __hip_atomic_load(p, __ATOMIC_RELAXED, __HIP_MEMORY_SCOPE_AGENT); }
; __device__ __forceinline__ void grid_barrier_impl(int wave, unsigned G, unsigned xcc, volatile LAS unsigned* st) {
;     ...
;         if (old == nloc - 1u) {
;             __hip_atomic_store(&g_xb[XB_CNT(xcc)], 0u, __ATOMIC_RELAXED, __HIP_MEMORY_SCOPE_AGENT);
;             __builtin_amdgcn_fence(__ATOMIC_RELEASE, "agent");
;             asm volatile("s_waitcnt vmcnt(0)" ::: "memory");
;             const unsigned tg = xb_ld(&g_xb[XB_TGEN]);
;             const unsigned o2 = __hip_atomic_fetch_add(&g_xb[XB_TCNT], 1u, __ATOMIC_ACQ_REL, __HIP_MEMORY_SCOPE_AGENT);
.LBB0_257:
	s_andn2_saveexec_b64 s[38:39], s[40:41]
	s_cbranch_execz .LBB0_270
	v_readlane_b32 s38, v253, 42
	v_readlane_b32 s39, v253, 43
	s_mov_b64 s[40:41], exec
	s_waitcnt vmcnt(0)
	v_mbcnt_lo_u32_b32 v2, s40, 0
	v_mbcnt_hi_u32_b32 v2, s41, v2
	v_cmp_eq_u32_e32 vcc, 0, v2
	global_store_dword v195, v195, s[38:39] sc1
	buffer_wbl2 sc1
	s_waitcnt vmcnt(0) lgkmcnt(0)
	s_waitcnt vmcnt(0)
	s_getpc_b64 s[38:39]
	s_add_u32 s38, s38, g_xb@rel32@lo+12548
	s_addc_u32 s39, s39, g_xb@rel32@hi+12556
	global_load_dword v1, v195, s[38:39] sc1
	s_and_saveexec_b64 s[42:43], vcc
	s_cbranch_execz .LBB0_260
	s_bcnt1_i32_b64 s40, s[40:41]
	s_getpc_b64 s[38:39]
	s_add_u32 s38, s38, g_xb@rel32@lo+12292
	s_addc_u32 s39, s39, g_xb@rel32@hi+12300
	v_mov_b32_e32 v3, s40
	s_nop 0
	s_waitcnt vmcnt(0)
	global_atomic_add v3, v195, v3, s[38:39] sc0
	s_waitcnt vmcnt(0)
	s_nop 0

; __device__ __forceinline__ void grid_barrier_impl(int wave, unsigned G, unsigned xcc, volatile LAS unsigned* st) {
;     ...
;             if (o2 == nx - 1u) { __hip_atomic_store(&g_xb[XB_TCNT], 0u, __ATOMIC_RELAXED, __HIP_MEMORY_SCOPE_AGENT); __hip_atomic_fetch_add(&g_xb[XB_TGEN], 1u, __ATOMIC_RELEASE, __HIP_MEMORY_SCOPE_AGENT); }
.LBB0_263:
	s_andn2_saveexec_b64 s[40:41], s[40:41]
	s_cbranch_execz .LBB0_267
	s_mov_b64 s[42:43], exec
	v_mbcnt_lo_u32_b32 v0, s42, 0
	v_mbcnt_hi_u32_b32 v0, s43, v0
	s_getpc_b64 s[38:39]
	s_add_u32 s38, s38, g_xb@rel32@lo+12292
	s_addc_u32 s39, s39, g_xb@rel32@hi+12300
	v_cmp_eq_u32_e32 vcc, 0, v0
	global_store_dword v195, v195, s[38:39] sc1
	s_and_saveexec_b64 s[44:45], vcc
	s_cbranch_execz .LBB0_266
	s_bcnt1_i32_b64 s42, s[42:43]
	s_getpc_b64 s[38:39]
	s_add_u32 s38, s38, g_xb@rel32@lo+12548
	s_addc_u32 s39, s39, g_xb@rel32@hi+12556
	v_mov_b32_e32 v0, s42
	s_nop 0
	s_waitcnt vmcnt(0)
	global_atomic_add v195, v0, s[38:39]

; __device__ __forceinline__ void grid_barrier_impl(int wave, unsigned G, unsigned xcc, volatile LAS unsigned* st) {
;     ...
;             __builtin_amdgcn_fence(__ATOMIC_ACQUIRE, "agent");
;             __hip_atomic_fetch_add(&g_xb[XB_GEN(xcc)], 1u, __ATOMIC_RELEASE, __HIP_MEMORY_SCOPE_AGENT);
.LBB0_267:
	s_or_b64 exec, exec, s[40:41]
	s_mov_b64 s[40:41], exec
	v_mbcnt_lo_u32_b32 v0, s40, 0
	v_mbcnt_hi_u32_b32 v0, s41, v0
	v_cmp_eq_u32_e32 vcc, 0, v0
	s_waitcnt vmcnt(0)
	buffer_inv sc1
	s_and_saveexec_b64 s[42:43], vcc
	s_cbranch_execz .LBB0_269
	s_bcnt1_i32_b64 s38, s[40:41]
	v_mov_b32_e32 v0, s38
	s_nop 0
	global_atomic_add v195, v0, s[94:95]

; __device__ __forceinline__ unsigned xb_ld(unsigned* p) { return __hip_atomic_load(p, __ATOMIC_RELAXED, __HIP_MEMORY_SCOPE_AGENT); }
; __device__ __forceinline__ void grid_barrier_impl(int wave, unsigned G, unsigned xcc, volatile LAS unsigned* st) {
;     ...
;         const unsigned gen = xb_ld(&g_xb[XB_GEN(xcc)]);
;         const unsigned old = __hip_atomic_fetch_add(&g_xb[XB_CNT(xcc)], 1u, __ATOMIC_ACQ_REL, __HIP_MEMORY_SCOPE_AGENT);
.LBB0_318:
	global_load_dword v2, v195, s[94:95] sc1
	s_mov_b64 s[42:43], exec
	v_mbcnt_lo_u32_b32 v3, s42, 0
	v_mbcnt_hi_u32_b32 v3, s43, v3
	v_cmp_eq_u32_e32 vcc, 0, v3
	s_and_saveexec_b64 s[44:45], vcc
	s_cbranch_execz .LBB0_320
	s_bcnt1_i32_b64 s38, s[42:43]
	v_mov_b32_e32 v4, s38
	v_readlane_b32 s38, v253, 42
	v_readlane_b32 s39, v253, 43
	s_nop 0
	s_waitcnt vmcnt(0) lgkmcnt(0)
	s_nop 2
	global_atomic_add v4, v195, v4, s[38:39] sc0
	s_waitcnt vmcnt(0)
	s_nop 0

; __device__ __forceinline__ unsigned xb_ld(unsigned* p) { return __hip_atomic_load(p, __ATOMIC_RELAXED, __HIP_MEMORY_SCOPE_AGENT); }
; __device__ __forceinline__ void grid_barrier_impl(int wave, unsigned G, unsigned xcc, volatile LAS unsigned* st) {
;     ...
;         if (old == nloc - 1u) {
;             __hip_atomic_store(&g_xb[XB_CNT(xcc)], 0u, __ATOMIC_RELAXED, __HIP_MEMORY_SCOPE_AGENT);
;             __builtin_amdgcn_fence(__ATOMIC_RELEASE, "agent");
;             asm volatile("s_waitcnt vmcnt(0)" ::: "memory");
;             const unsigned tg = xb_ld(&g_xb[XB_TGEN]);
;             const unsigned o2 = __hip_atomic_fetch_add(&g_xb[XB_TCNT], 1u, __ATOMIC_ACQ_REL, __HIP_MEMORY_SCOPE_AGENT);
.LBB0_324:
	s_andn2_saveexec_b64 s[38:39], s[42:43]
	s_cbranch_execz .LBB0_337
	v_readlane_b32 s38, v253, 42
	v_readlane_b32 s39, v253, 43
	s_mov_b64 s[42:43], exec
	s_waitcnt vmcnt(0)
	v_mbcnt_lo_u32_b32 v2, s42, 0
	v_mbcnt_hi_u32_b32 v2, s43, v2
	v_cmp_eq_u32_e32 vcc, 0, v2
	global_store_dword v195, v195, s[38:39] sc1
	buffer_wbl2 sc1
	s_waitcnt vmcnt(0) lgkmcnt(0)
	s_waitcnt vmcnt(0)
	s_getpc_b64 s[38:39]
	s_add_u32 s38, s38, g_xb@rel32@lo+12548
	s_addc_u32 s39, s39, g_xb@rel32@hi+12556
	global_load_dword v1, v195, s[38:39] sc1
	s_and_saveexec_b64 s[44:45], vcc
	s_cbranch_execz .LBB0_327
	s_bcnt1_i32_b64 s40, s[42:43]
	s_getpc_b64 s[38:39]
	s_add_u32 s38, s38, g_xb@rel32@lo+12292
	s_addc_u32 s39, s39, g_xb@rel32@hi+12300
	v_mov_b32_e32 v3, s40
	s_nop 0
	s_waitcnt vmcnt(0)
	global_atomic_add v3, v195, v3, s[38:39] sc0
	s_waitcnt vmcnt(0)
	s_nop 0

; __device__ __forceinline__ void grid_barrier_impl(int wave, unsigned G, unsigned xcc, volatile LAS unsigned* st) {
;     ...
;             if (o2 == nx - 1u) { __hip_atomic_store(&g_xb[XB_TCNT], 0u, __ATOMIC_RELAXED, __HIP_MEMORY_SCOPE_AGENT); __hip_atomic_fetch_add(&g_xb[XB_TGEN], 1u, __ATOMIC_RELEASE, __HIP_MEMORY_SCOPE_AGENT); }
.LBB0_330:
	s_andn2_saveexec_b64 s[42:43], s[42:43]
	s_cbranch_execz .LBB0_334
	s_mov_b64 s[44:45], exec
	v_mbcnt_lo_u32_b32 v0, s44, 0
	v_mbcnt_hi_u32_b32 v0, s45, v0
	s_getpc_b64 s[38:39]
	s_add_u32 s38, s38, g_xb@rel32@lo+12292
	s_addc_u32 s39, s39, g_xb@rel32@hi+12300
	v_cmp_eq_u32_e32 vcc, 0, v0
	global_store_dword v195, v195, s[38:39] sc1
	s_and_saveexec_b64 s[46:47], vcc
	s_cbranch_execz .LBB0_333
	s_bcnt1_i32_b64 s40, s[44:45]
	s_getpc_b64 s[38:39]
	s_add_u32 s38, s38, g_xb@rel32@lo+12548
	s_addc_u32 s39, s39, g_xb@rel32@hi+12556
	v_mov_b32_e32 v0, s40
	s_nop 0
	s_waitcnt vmcnt(0)
	global_atomic_add v195, v0, s[38:39]

; __device__ __forceinline__ void grid_barrier_impl(int wave, unsigned G, unsigned xcc, volatile LAS unsigned* st) {
;     ...
;             __builtin_amdgcn_fence(__ATOMIC_ACQUIRE, "agent");
;             __hip_atomic_fetch_add(&g_xb[XB_GEN(xcc)], 1u, __ATOMIC_RELEASE, __HIP_MEMORY_SCOPE_AGENT);
.LBB0_334:
	s_or_b64 exec, exec, s[42:43]
	s_mov_b64 s[42:43], exec
	v_mbcnt_lo_u32_b32 v0, s42, 0
	v_mbcnt_hi_u32_b32 v0, s43, v0
	v_cmp_eq_u32_e32 vcc, 0, v0
	s_waitcnt vmcnt(0)
	buffer_inv sc1
	s_and_saveexec_b64 s[44:45], vcc
	s_cbranch_execz .LBB0_336
	s_bcnt1_i32_b64 s38, s[42:43]
	v_mov_b32_e32 v0, s38
	s_nop 0
	global_atomic_add v195, v0, s[94:95]

; __device__ __forceinline__ unsigned xb_ld(unsigned* p) { return __hip_atomic_load(p, __ATOMIC_RELAXED, __HIP_MEMORY_SCOPE_AGENT); }
; __device__ __forceinline__ void grid_barrier_impl(int wave, unsigned G, unsigned xcc, volatile LAS unsigned* st) {
;     ...
;         const unsigned gen = xb_ld(&g_xb[XB_GEN(xcc)]);
;         const unsigned old = __hip_atomic_fetch_add(&g_xb[XB_CNT(xcc)], 1u, __ATOMIC_ACQ_REL, __HIP_MEMORY_SCOPE_AGENT);
.LBB0_1011:
	global_load_dword v2, v195, s[94:95] sc1
	s_mov_b64 s[44:45], exec
	v_mbcnt_lo_u32_b32 v3, s44, 0
	v_mbcnt_hi_u32_b32 v3, s45, v3
	v_cmp_eq_u32_e32 vcc, 0, v3
	s_and_saveexec_b64 s[46:47], vcc
	s_cbranch_execz .LBB0_1013
	s_bcnt1_i32_b64 s38, s[44:45]
	v_mov_b32_e32 v4, s38
	v_readlane_b32 s38, v253, 42
	v_readlane_b32 s39, v253, 43
	s_nop 0
	s_waitcnt vmcnt(0) lgkmcnt(0)
	s_nop 2
	global_atomic_add v4, v195, v4, s[38:39] sc0
	s_waitcnt vmcnt(0)
	s_nop 0

; __device__ __forceinline__ unsigned xb_ld(unsigned* p) { return __hip_atomic_load(p, __ATOMIC_RELAXED, __HIP_MEMORY_SCOPE_AGENT); }
; __device__ __forceinline__ void grid_barrier_impl(int wave, unsigned G, unsigned xcc, volatile LAS unsigned* st) {
;     ...
;         if (old == nloc - 1u) {
;             __hip_atomic_store(&g_xb[XB_CNT(xcc)], 0u, __ATOMIC_RELAXED, __HIP_MEMORY_SCOPE_AGENT);
;             __builtin_amdgcn_fence(__ATOMIC_RELEASE, "agent");
;             asm volatile("s_waitcnt vmcnt(0)" ::: "memory");
;             const unsigned tg = xb_ld(&g_xb[XB_TGEN]);
;             const unsigned o2 = __hip_atomic_fetch_add(&g_xb[XB_TCNT], 1u, __ATOMIC_ACQ_REL, __HIP_MEMORY_SCOPE_AGENT);
.LBB0_1017:
	s_andn2_saveexec_b64 s[38:39], s[44:45]
	s_cbranch_execz .LBB0_1030
	v_readlane_b32 s38, v253, 42
	v_readlane_b32 s39, v253, 43
	s_mov_b64 s[44:45], exec
	s_waitcnt vmcnt(0)
	v_mbcnt_lo_u32_b32 v2, s44, 0
	v_mbcnt_hi_u32_b32 v2, s45, v2
	v_cmp_eq_u32_e32 vcc, 0, v2
	global_store_dword v195, v195, s[38:39] sc1
	buffer_wbl2 sc1
	s_waitcnt vmcnt(0) lgkmcnt(0)
	s_waitcnt vmcnt(0)
	s_getpc_b64 s[38:39]
	s_add_u32 s38, s38, g_xb@rel32@lo+12548
	s_addc_u32 s39, s39, g_xb@rel32@hi+12556
	global_load_dword v1, v195, s[38:39] sc1
	s_and_saveexec_b64 s[46:47], vcc
	s_cbranch_execz .LBB0_1020
	s_bcnt1_i32_b64 s40, s[44:45]
	s_getpc_b64 s[38:39]
	s_add_u32 s38, s38, g_xb@rel32@lo+12292
	s_addc_u32 s39, s39, g_xb@rel32@hi+12300
	v_mov_b32_e32 v3, s40
	s_nop 0
	s_waitcnt vmcnt(0)
	global_atomic_add v3, v195, v3, s[38:39] sc0
	s_waitcnt vmcnt(0)
	s_nop 0

; __device__ __forceinline__ void grid_barrier_impl(int wave, unsigned G, unsigned xcc, volatile LAS unsigned* st) {
;     ...
;             if (o2 == nx - 1u) { __hip_atomic_store(&g_xb[XB_TCNT], 0u, __ATOMIC_RELAXED, __HIP_MEMORY_SCOPE_AGENT); __hip_atomic_fetch_add(&g_xb[XB_TGEN], 1u, __ATOMIC_RELEASE, __HIP_MEMORY_SCOPE_AGENT); }
.LBB0_1023:
	s_andn2_saveexec_b64 s[44:45], s[44:45]
	s_cbranch_execz .LBB0_1027
	s_mov_b64 s[46:47], exec
	v_mbcnt_lo_u32_b32 v0, s46, 0
	v_mbcnt_hi_u32_b32 v0, s47, v0
	s_getpc_b64 s[38:39]
	s_add_u32 s38, s38, g_xb@rel32@lo+12292
	s_addc_u32 s39, s39, g_xb@rel32@hi+12300
	v_cmp_eq_u32_e32 vcc, 0, v0
	global_store_dword v195, v195, s[38:39] sc1
	s_and_saveexec_b64 s[48:49], vcc
	s_cbranch_execz .LBB0_1026
	s_bcnt1_i32_b64 s40, s[46:47]
	s_getpc_b64 s[38:39]
	s_add_u32 s38, s38, g_xb@rel32@lo+12548
	s_addc_u32 s39, s39, g_xb@rel32@hi+12556
	v_mov_b32_e32 v0, s40
	s_nop 0
	s_waitcnt vmcnt(0)
	global_atomic_add v195, v0, s[38:39]

; __device__ __forceinline__ void grid_barrier_impl(int wave, unsigned G, unsigned xcc, volatile LAS unsigned* st) {
;     ...
;             __builtin_amdgcn_fence(__ATOMIC_ACQUIRE, "agent");
;             __hip_atomic_fetch_add(&g_xb[XB_GEN(xcc)], 1u, __ATOMIC_RELEASE, __HIP_MEMORY_SCOPE_AGENT);
.LBB0_1027:
	s_or_b64 exec, exec, s[44:45]
	s_mov_b64 s[44:45], exec
	v_mbcnt_lo_u32_b32 v0, s44, 0
	v_mbcnt_hi_u32_b32 v0, s45, v0
	v_cmp_eq_u32_e32 vcc, 0, v0
	s_waitcnt vmcnt(0)
	buffer_inv sc1
	s_and_saveexec_b64 s[46:47], vcc
	s_cbranch_execz .LBB0_1029
	s_bcnt1_i32_b64 s38, s[44:45]
	v_mov_b32_e32 v0, s38
	s_nop 0
	global_atomic_add v195, v0, s[94:95]

; __device__ __forceinline__ unsigned xb_ld(unsigned* p) { return __hip_atomic_load(p, __ATOMIC_RELAXED, __HIP_MEMORY_SCOPE_AGENT); }
; __device__ __forceinline__ void grid_barrier_impl(int wave, unsigned G, unsigned xcc, volatile LAS unsigned* st) {
;     ...
;         const unsigned gen = xb_ld(&g_xb[XB_GEN(xcc)]);
;         const unsigned old = __hip_atomic_fetch_add(&g_xb[XB_CNT(xcc)], 1u, __ATOMIC_ACQ_REL, __HIP_MEMORY_SCOPE_AGENT);
.LBB0_1718:
	global_load_dword v2, v195, s[94:95] sc1
	s_mov_b64 s[38:39], exec
	v_mbcnt_lo_u32_b32 v3, s38, 0
	v_mbcnt_hi_u32_b32 v3, s39, v3
	v_cmp_eq_u32_e32 vcc, 0, v3
	s_and_saveexec_b64 s[42:43], vcc
	s_cbranch_execz .LBB0_1720
	s_bcnt1_i32_b64 s38, s[38:39]
	v_mov_b32_e32 v4, s38
	v_readlane_b32 s38, v253, 42
	v_readlane_b32 s39, v253, 43
	s_nop 0
	s_waitcnt vmcnt(0) lgkmcnt(0)
	s_nop 2
	global_atomic_add v4, v195, v4, s[38:39] sc0
	s_waitcnt vmcnt(0)
	s_nop 0

; __device__ __forceinline__ unsigned xb_ld(unsigned* p) { return __hip_atomic_load(p, __ATOMIC_RELAXED, __HIP_MEMORY_SCOPE_AGENT); }
; __device__ __forceinline__ void grid_barrier_impl(int wave, unsigned G, unsigned xcc, volatile LAS unsigned* st) {
;     ...
;         if (old == nloc - 1u) {
;             __hip_atomic_store(&g_xb[XB_CNT(xcc)], 0u, __ATOMIC_RELAXED, __HIP_MEMORY_SCOPE_AGENT);
;             __builtin_amdgcn_fence(__ATOMIC_RELEASE, "agent");
;             asm volatile("s_waitcnt vmcnt(0)" ::: "memory");
;             const unsigned tg = xb_ld(&g_xb[XB_TGEN]);
;             const unsigned o2 = __hip_atomic_fetch_add(&g_xb[XB_TCNT], 1u, __ATOMIC_ACQ_REL, __HIP_MEMORY_SCOPE_AGENT);
.LBB0_1724:
	s_andn2_saveexec_b64 s[38:39], s[38:39]
	s_cbranch_execz .LBB0_1737
	v_readlane_b32 s40, v253, 42
	v_readlane_b32 s41, v253, 43
	s_mov_b64 s[38:39], exec
	s_waitcnt vmcnt(0)
	v_mbcnt_lo_u32_b32 v2, s38, 0
	v_mbcnt_hi_u32_b32 v2, s39, v2
	v_cmp_eq_u32_e32 vcc, 0, v2
	global_store_dword v195, v195, s[40:41] sc1
	buffer_wbl2 sc1
	s_waitcnt vmcnt(0) lgkmcnt(0)
	s_waitcnt vmcnt(0)
	s_getpc_b64 s[40:41]
	s_add_u32 s40, s40, g_xb@rel32@lo+12548
	s_addc_u32 s41, s41, g_xb@rel32@hi+12556
	global_load_dword v1, v195, s[40:41] sc1
	s_and_saveexec_b64 s[42:43], vcc
	s_cbranch_execz .LBB0_1727
	s_bcnt1_i32_b64 s40, s[38:39]
	s_getpc_b64 s[38:39]
	s_add_u32 s38, s38, g_xb@rel32@lo+12292
	s_addc_u32 s39, s39, g_xb@rel32@hi+12300
	v_mov_b32_e32 v3, s40
	s_nop 0
	s_waitcnt vmcnt(0)
	global_atomic_add v3, v195, v3, s[38:39] sc0
	s_waitcnt vmcnt(0)
	s_nop 0

; __device__ __forceinline__ void grid_barrier_impl(int wave, unsigned G, unsigned xcc, volatile LAS unsigned* st) {
;     ...
;             if (o2 == nx - 1u) { __hip_atomic_store(&g_xb[XB_TCNT], 0u, __ATOMIC_RELAXED, __HIP_MEMORY_SCOPE_AGENT); __hip_atomic_fetch_add(&g_xb[XB_TGEN], 1u, __ATOMIC_RELEASE, __HIP_MEMORY_SCOPE_AGENT); }
.LBB0_1730:
	s_andn2_saveexec_b64 s[38:39], s[38:39]
	s_cbranch_execz .LBB0_1734
	s_mov_b64 s[42:43], exec
	v_mbcnt_lo_u32_b32 v0, s42, 0
	v_mbcnt_hi_u32_b32 v0, s43, v0
	s_getpc_b64 s[40:41]
	s_add_u32 s40, s40, g_xb@rel32@lo+12292
	s_addc_u32 s41, s41, g_xb@rel32@hi+12300
	v_cmp_eq_u32_e32 vcc, 0, v0
	global_store_dword v195, v195, s[40:41] sc1
	s_and_saveexec_b64 s[44:45], vcc
	s_cbranch_execz .LBB0_1733
	s_bcnt1_i32_b64 s42, s[42:43]
	s_getpc_b64 s[40:41]
	s_add_u32 s40, s40, g_xb@rel32@lo+12548
	s_addc_u32 s41, s41, g_xb@rel32@hi+12556
	v_mov_b32_e32 v0, s42
	s_nop 0
	s_waitcnt vmcnt(0)
	global_atomic_add v195, v0, s[40:41]

; __device__ __forceinline__ void grid_barrier_impl(int wave, unsigned G, unsigned xcc, volatile LAS unsigned* st) {
;     ...
;             __builtin_amdgcn_fence(__ATOMIC_ACQUIRE, "agent");
;             __hip_atomic_fetch_add(&g_xb[XB_GEN(xcc)], 1u, __ATOMIC_RELEASE, __HIP_MEMORY_SCOPE_AGENT);
.LBB0_1734:
	s_or_b64 exec, exec, s[38:39]
	s_mov_b64 s[38:39], exec
	v_mbcnt_lo_u32_b32 v0, s38, 0
	v_mbcnt_hi_u32_b32 v0, s39, v0
	v_cmp_eq_u32_e32 vcc, 0, v0
	s_waitcnt vmcnt(0)
	buffer_inv sc1
	s_and_saveexec_b64 s[42:43], vcc
	s_cbranch_execz .LBB0_1736
	s_bcnt1_i32_b64 s38, s[38:39]
	v_mov_b32_e32 v0, s38
	s_nop 0
	global_atomic_add v195, v0, s[94:95]

; __device__ __forceinline__ unsigned xb_ld(unsigned* p) { return __hip_atomic_load(p, __ATOMIC_RELAXED, __HIP_MEMORY_SCOPE_AGENT); }
; __device__ __forceinline__ void grid_barrier_impl(int wave, unsigned G, unsigned xcc, volatile LAS unsigned* st) {
;     ...
;         const unsigned gen = xb_ld(&g_xb[XB_GEN(xcc)]);
;         const unsigned old = __hip_atomic_fetch_add(&g_xb[XB_CNT(xcc)], 1u, __ATOMIC_ACQ_REL, __HIP_MEMORY_SCOPE_AGENT);
.LBB0_1785:
	global_load_dword v2, v195, s[94:95] sc1
	s_mov_b64 s[36:37], exec
	v_mbcnt_lo_u32_b32 v3, s36, 0
	v_mbcnt_hi_u32_b32 v3, s37, v3
	v_cmp_eq_u32_e32 vcc, 0, v3
	s_and_saveexec_b64 s[38:39], vcc
	s_cbranch_execz .LBB0_1787
	s_bcnt1_i32_b64 s36, s[36:37]
	v_mov_b32_e32 v4, s36
	v_readlane_b32 s36, v253, 42
	v_readlane_b32 s37, v253, 43
	s_nop 0
	s_waitcnt vmcnt(0) lgkmcnt(0)
	s_nop 2
	global_atomic_add v4, v195, v4, s[36:37] sc0
	s_waitcnt vmcnt(0)
	s_nop 0

; __device__ __forceinline__ unsigned xb_ld(unsigned* p) { return __hip_atomic_load(p, __ATOMIC_RELAXED, __HIP_MEMORY_SCOPE_AGENT); }
; __device__ __forceinline__ void grid_barrier_impl(int wave, unsigned G, unsigned xcc, volatile LAS unsigned* st) {
;     ...
;         if (old == nloc - 1u) {
;             __hip_atomic_store(&g_xb[XB_CNT(xcc)], 0u, __ATOMIC_RELAXED, __HIP_MEMORY_SCOPE_AGENT);
;             __builtin_amdgcn_fence(__ATOMIC_RELEASE, "agent");
;             asm volatile("s_waitcnt vmcnt(0)" ::: "memory");
;             const unsigned tg = xb_ld(&g_xb[XB_TGEN]);
;             const unsigned o2 = __hip_atomic_fetch_add(&g_xb[XB_TCNT], 1u, __ATOMIC_ACQ_REL, __HIP_MEMORY_SCOPE_AGENT);
.LBB0_1792:
	v_readlane_b32 s38, v253, 42
	v_readlane_b32 s39, v253, 43
	s_mov_b64 s[36:37], exec
	s_waitcnt vmcnt(0)
	v_mbcnt_lo_u32_b32 v2, s36, 0
	v_mbcnt_hi_u32_b32 v2, s37, v2
	v_cmp_eq_u32_e32 vcc, 0, v2
	global_store_dword v195, v195, s[38:39] sc1
	buffer_wbl2 sc1
	s_waitcnt vmcnt(0) lgkmcnt(0)
	s_waitcnt vmcnt(0)
	s_getpc_b64 s[38:39]
	s_add_u32 s38, s38, g_xb@rel32@lo+12548
	s_addc_u32 s39, s39, g_xb@rel32@hi+12556
	global_load_dword v1, v195, s[38:39] sc1
	s_and_saveexec_b64 s[38:39], vcc
	s_cbranch_execz .LBB0_1794
	s_bcnt1_i32_b64 s40, s[36:37]
	s_getpc_b64 s[36:37]
	s_add_u32 s36, s36, g_xb@rel32@lo+12292
	s_addc_u32 s37, s37, g_xb@rel32@hi+12300
	v_mov_b32_e32 v3, s40
	s_nop 0
	s_waitcnt vmcnt(0)
	global_atomic_add v3, v195, v3, s[36:37] sc0
	s_waitcnt vmcnt(0)
	s_nop 0

; __device__ __forceinline__ void grid_barrier_impl(int wave, unsigned G, unsigned xcc, volatile LAS unsigned* st) {
;     ...
;             if (o2 == nx - 1u) { __hip_atomic_store(&g_xb[XB_TCNT], 0u, __ATOMIC_RELAXED, __HIP_MEMORY_SCOPE_AGENT); __hip_atomic_fetch_add(&g_xb[XB_TGEN], 1u, __ATOMIC_RELEASE, __HIP_MEMORY_SCOPE_AGENT); }
.LBB0_1797:
	s_andn2_saveexec_b64 s[36:37], s[36:37]
	s_cbranch_execz .LBB0_1801
	s_mov_b64 s[38:39], exec
	v_mbcnt_lo_u32_b32 v0, s38, 0
	v_mbcnt_hi_u32_b32 v0, s39, v0
	s_getpc_b64 s[40:41]
	s_add_u32 s40, s40, g_xb@rel32@lo+12292
	s_addc_u32 s41, s41, g_xb@rel32@hi+12300
	v_cmp_eq_u32_e32 vcc, 0, v0
	global_store_dword v195, v195, s[40:41] sc1
	s_and_saveexec_b64 s[40:41], vcc
	s_cbranch_execz .LBB0_1800
	s_bcnt1_i32_b64 s42, s[38:39]
	s_getpc_b64 s[38:39]
	s_add_u32 s38, s38, g_xb@rel32@lo+12548
	s_addc_u32 s39, s39, g_xb@rel32@hi+12556
	v_mov_b32_e32 v0, s42
	s_nop 0
	s_waitcnt vmcnt(0)
	global_atomic_add v195, v0, s[38:39]

; __device__ __forceinline__ void grid_barrier_impl(int wave, unsigned G, unsigned xcc, volatile LAS unsigned* st) {
;     ...
;             __hip_atomic_fetch_add(&g_xb[XB_GEN(xcc)], 1u, __ATOMIC_RELEASE, __HIP_MEMORY_SCOPE_AGENT);
.LBB0_1802:
	s_bcnt1_i32_b64 s36, s[36:37]
	v_mov_b32_e32 v0, s36
	s_nop 0
	global_atomic_add v195, v0, s[94:95]
	s_getpc_b64 s[98:99]
